# v12 plus mod0 phase: 4 rows of loads in flight per wave (batched 16 loads, counted vmcnt) instead of one row per iteration
# speedup vs baseline: 1.0010x; 1.0010x over previous
; DI void mod0_row(const float* src, bf16_t* dst, int c0, const float4 sc0, const float4 sc1, const float4 sc2, const float4 sc3,
;                  const float4 sh0, const float4 sh1, const float4 sh2, const float4 sh3) {
;   const f32x4 v0 = __builtin_nontemporal_load((const f32x4*)(src + c0)), v1 = __builtin_nontemporal_load((const f32x4*)(src + c0 + 256));
;   const f32x4 v2 = __builtin_nontemporal_load((const f32x4*)(src + c0 + 512)), v3 = __builtin_nontemporal_load((const f32x4*)(src + c0 + 768));
;   uint2 o;
;   o.x = pk2(v0[0] * (1.f + sc0.x) + sh0.x, v0[1] * (1.f + sc0.y) + sh0.y); o.y = pk2(v0[2] * (1.f + sc0.z) + sh0.z, v0[3] * (1.f + sc0.w) + sh0.w);
;   *(uint2*)(dst + c0) = o;
;   o.x = pk2(v1[0] * (1.f + sc1.x) + sh1.x, v1[1] * (1.f + sc1.y) + sh1.y); o.y = pk2(v1[2] * (1.f + sc1.z) + sh1.z, v1[3] * (1.f + sc1.w) + sh1.w);
;   *(uint2*)(dst + c0 + 256) = o;
;   o.x = pk2(v2[0] * (1.f + sc2.x) + sh2.x, v2[1] * (1.f + sc2.y) + sh2.y); o.y = pk2(v2[2] * (1.f + sc2.z) + sh2.z, v2[3] * (1.f + sc2.w) + sh2.w);
;   *(uint2*)(dst + c0 + 512) = o;
;   o.x = pk2(v3[0] * (1.f + sc3.x) + sh3.x, v3[1] * (1.f + sc3.y) + sh3.y); o.y = pk2(v3[2] * (1.f + sc3.z) + sh3.z, v3[3] * (1.f + sc3.w) + sh3.w);
;   *(uint2*)(dst + c0 + 768) = o;
; }
; DI void phase_mod0(const Params& p) {
;   const int tid = opaque_tid(), lane = tid & 63, wave = __builtin_amdgcn_readfirstlane(tid >> 6);
;   const int c0 = lane * 4;
;   const int nw = gridDim.x * 8, gw = blockIdx.x * 8 + wave;
;   const int r_lo = (int)(((long)gw * TT) / nw), r_hi = (int)(((long)(gw + 1) * TT) / nw);
;   int bcur = -1;
;   float4 sc0, sc1, sc2, sc3, sh0, sh1, sh2, sh3;
;   sc0 = sc1 = sc2 = sc3 = sh0 = sh1 = sh2 = sh3 = make_float4(0.f, 0.f, 0.f, 0.f);
; #pragma unroll 1
;   for (int row = r_lo; row < r_hi; ++row) {
;     const bool isctx = row >= TL;
;     const int b = isctx ? 32 : (row >> 11);
;     if (b != bcur) {
;       bcur = b;
;       const float* md = p.mod + (size_t)b * 3072;
;       sh0 = *(const float4*)(md + c0); sh1 = *(const float4*)(md + c0 + 256); sh2 = *(const float4*)(md + c0 + 512); sh3 = *(const float4*)(md + c0 + 768);
;       sc0 = *(const float4*)(md + 1024 + c0); sc1 = *(const float4*)(md + 1024 + c0 + 256); sc2 = *(const float4*)(md + 1024 + c0 + 512); sc3 = *(const float4*)(md + 1024 + c0 + 768);
;     }
.LBB0_26:
	s_add_i32 s100, s6, 4
	s_cmp_gt_i32 s100, s8
	s_cbranch_scc1 .Lmod0_slow
	s_add_i32 s100, s6, 3
	s_min_i32 s100, s100, 0x10000
	s_ashr_i32 s100, s100, 11
	s_cmp_lg_u32 s100, s2
	s_cbranch_scc0 .Lmod0_fast
.Lmod0_slow:
	s_cmp_lt_i32 s6, 0x10000
	s_mov_b64 s[14:15], s[6:7]
	s_mov_b64 s[12:13], s[10:11]
	s_cbranch_scc1 .LBB0_23
	s_add_i32 s78, s6, 0xffff0000
	s_lshl_b64 s[12:13], s[78:79], 12
	s_add_u32 s12, s56, s12
	s_mov_b32 s78, s6
	s_addc_u32 s13, s57, s13
	s_mov_b64 s[14:15], s[78:79]
	s_branch .LBB0_23
.Lmod0_fast:
	s_cmp_lt_i32 s6, 0x10000
	s_mov_b64 s[14:15], s[6:7]
	s_mov_b64 s[12:13], s[10:11]
	s_cbranch_scc1 .Lmod0_f2
	s_add_i32 s78, s6, 0xffff0000
	s_lshl_b64 s[12:13], s[78:79], 12
	s_add_u32 s12, s56, s12
	s_mov_b32 s78, s6
	s_addc_u32 s13, s57, s13
	s_mov_b64 s[14:15], s[78:79]
.Lmod0_f2:
	s_lshl_b64 s[14:15], s[14:15], 11
	global_load_dwordx4 v[56:59], v0, s[12:13] nt
	global_load_dwordx4 v[60:63], v0, s[12:13] offset:1024 nt
	global_load_dwordx4 v[64:67], v0, s[12:13] offset:2048 nt
	global_load_dwordx4 v[68:71], v0, s[12:13] offset:3072 nt
	s_add_u32 s12, s12, 0x1000
	s_addc_u32 s13, s13, 0
	global_load_dwordx4 v[72:75], v0, s[12:13] nt
	global_load_dwordx4 v[76:79], v0, s[12:13] offset:1024 nt
	global_load_dwordx4 v[80:83], v0, s[12:13] offset:2048 nt
	global_load_dwordx4 v[84:87], v0, s[12:13] offset:3072 nt
	s_add_u32 s12, s12, 0x1000
	s_addc_u32 s13, s13, 0
	global_load_dwordx4 v[88:91], v0, s[12:13] nt
	global_load_dwordx4 v[92:95], v0, s[12:13] offset:1024 nt
	global_load_dwordx4 v[96:99], v0, s[12:13] offset:2048 nt
	global_load_dwordx4 v[100:103], v0, s[12:13] offset:3072 nt
	s_add_u32 s12, s12, 0x1000
	s_addc_u32 s13, s13, 0
	global_load_dwordx4 v[148:151], v0, s[12:13] nt
	global_load_dwordx4 v[152:155], v0, s[12:13] offset:1024 nt
	global_load_dwordx4 v[156:159], v0, s[12:13] offset:2048 nt
	global_load_dwordx4 v[160:163], v0, s[12:13] offset:3072 nt
	s_movk_i32 s100, 0x800
	s_mov_b32 s101, 0
	v_lshl_add_u64 v[104:105], v[34:35], 0, s[14:15]
	s_waitcnt vmcnt(16)
	v_pk_add_f32 v[108:109], v[22:23], 1.0 op_sel_hi:[1,0]
	v_pk_add_f32 v[110:111], v[24:25], 1.0 op_sel_hi:[1,0]
	v_pk_add_f32 v[112:113], v[10:11], 1.0 op_sel_hi:[1,0]
	v_pk_add_f32 v[114:115], v[12:13], 1.0 op_sel_hi:[1,0]
	v_pk_add_f32 v[116:117], v[18:19], 1.0 op_sel_hi:[1,0]
	v_pk_add_f32 v[118:119], v[20:21], 1.0 op_sel_hi:[1,0]
	v_pk_add_f32 v[120:121], v[30:31], 1.0 op_sel_hi:[1,0]
	v_pk_add_f32 v[122:123], v[32:33], 1.0 op_sel_hi:[1,0]
	s_waitcnt vmcnt(15)
	v_pk_fma_f32 v[124:125], v[108:109], v[56:57], v[2:3]
	v_pk_fma_f32 v[126:127], v[110:111], v[58:59], v[4:5]
	v_cvt_pk_bf16_f32 v128, v124, v125
	v_cvt_pk_bf16_f32 v129, v126, v127
	global_store_dwordx2 v[104:105], v[128:129], off
	s_waitcnt vmcnt(15)
	v_pk_fma_f32 v[124:125], v[112:113], v[60:61], v[6:7]
	v_pk_fma_f32 v[126:127], v[114:115], v[62:63], v[8:9]
	v_cvt_pk_bf16_f32 v130, v124, v125
	v_cvt_pk_bf16_f32 v131, v126, v127
	global_store_dwordx2 v[104:105], v[130:131], off offset:512
	s_waitcnt vmcnt(15)
	v_pk_fma_f32 v[124:125], v[116:117], v[64:65], v[14:15]
	v_pk_fma_f32 v[126:127], v[118:119], v[66:67], v[16:17]
	v_cvt_pk_bf16_f32 v128, v124, v125
	v_cvt_pk_bf16_f32 v129, v126, v127
	global_store_dwordx2 v[104:105], v[128:129], off offset:1024
	s_waitcnt vmcnt(15)
	v_pk_fma_f32 v[124:125], v[120:121], v[68:69], v[26:27]
	v_pk_fma_f32 v[126:127], v[122:123], v[70:71], v[28:29]
	v_cvt_pk_bf16_f32 v130, v124, v125
	v_cvt_pk_bf16_f32 v131, v126, v127
	global_store_dwordx2 v[104:105], v[130:131], off offset:1536
	v_lshl_add_u64 v[104:105], v[104:105], 0, s[100:101]
	s_waitcnt vmcnt(15)
	v_pk_fma_f32 v[124:125], v[108:109], v[72:73], v[2:3]
	v_pk_fma_f32 v[126:127], v[110:111], v[74:75], v[4:5]
	v_cvt_pk_bf16_f32 v128, v124, v125
	v_cvt_pk_bf16_f32 v129, v126, v127
	global_store_dwordx2 v[104:105], v[128:129], off
	s_waitcnt vmcnt(15)
	v_pk_fma_f32 v[124:125], v[112:113], v[76:77], v[6:7]
	v_pk_fma_f32 v[126:127], v[114:115], v[78:79], v[8:9]
	v_cvt_pk_bf16_f32 v130, v124, v125
	v_cvt_pk_bf16_f32 v131, v126, v127
	global_store_dwordx2 v[104:105], v[130:131], off offset:512
	s_waitcnt vmcnt(15)
	v_pk_fma_f32 v[124:125], v[116:117], v[80:81], v[14:15]
	v_pk_fma_f32 v[126:127], v[118:119], v[82:83], v[16:17]
	v_cvt_pk_bf16_f32 v128, v124, v125
	v_cvt_pk_bf16_f32 v129, v126, v127
	global_store_dwordx2 v[104:105], v[128:129], off offset:1024
	s_waitcnt vmcnt(15)
	v_pk_fma_f32 v[124:125], v[120:121], v[84:85], v[26:27]
	v_pk_fma_f32 v[126:127], v[122:123], v[86:87], v[28:29]
	v_cvt_pk_bf16_f32 v130, v124, v125
	v_cvt_pk_bf16_f32 v131, v126, v127
	global_store_dwordx2 v[104:105], v[130:131], off offset:1536
	v_lshl_add_u64 v[104:105], v[104:105], 0, s[100:101]
	s_waitcnt vmcnt(15)
	v_pk_fma_f32 v[124:125], v[108:109], v[88:89], v[2:3]
	v_pk_fma_f32 v[126:127], v[110:111], v[90:91], v[4:5]
	v_cvt_pk_bf16_f32 v128, v124, v125
	v_cvt_pk_bf16_f32 v129, v126, v127
	global_store_dwordx2 v[104:105], v[128:129], off
	s_waitcnt vmcnt(15)
	v_pk_fma_f32 v[124:125], v[112:113], v[92:93], v[6:7]
	v_pk_fma_f32 v[126:127], v[114:115], v[94:95], v[8:9]
	v_cvt_pk_bf16_f32 v130, v124, v125
	v_cvt_pk_bf16_f32 v131, v126, v127
	global_store_dwordx2 v[104:105], v[130:131], off offset:512
	s_waitcnt vmcnt(15)
	v_pk_fma_f32 v[124:125], v[116:117], v[96:97], v[14:15]
	v_pk_fma_f32 v[126:127], v[118:119], v[98:99], v[16:17]
	v_cvt_pk_bf16_f32 v128, v124, v125
	v_cvt_pk_bf16_f32 v129, v126, v127
	global_store_dwordx2 v[104:105], v[128:129], off offset:1024
	s_waitcnt vmcnt(15)
	v_pk_fma_f32 v[124:125], v[120:121], v[100:101], v[26:27]
	v_pk_fma_f32 v[126:127], v[122:123], v[102:103], v[28:29]
	v_cvt_pk_bf16_f32 v130, v124, v125
	v_cvt_pk_bf16_f32 v131, v126, v127
	global_store_dwordx2 v[104:105], v[130:131], off offset:1536
	v_lshl_add_u64 v[104:105], v[104:105], 0, s[100:101]
	s_waitcnt vmcnt(15)
	v_pk_fma_f32 v[124:125], v[108:109], v[148:149], v[2:3]
	v_pk_fma_f32 v[126:127], v[110:111], v[150:151], v[4:5]
	v_cvt_pk_bf16_f32 v128, v124, v125
	v_cvt_pk_bf16_f32 v129, v126, v127
	global_store_dwordx2 v[104:105], v[128:129], off
	s_waitcnt vmcnt(15)
	v_pk_fma_f32 v[124:125], v[112:113], v[152:153], v[6:7]
	v_pk_fma_f32 v[126:127], v[114:115], v[154:155], v[8:9]
	v_cvt_pk_bf16_f32 v130, v124, v125
	v_cvt_pk_bf16_f32 v131, v126, v127
	global_store_dwordx2 v[104:105], v[130:131], off offset:512
	s_waitcnt vmcnt(15)
	v_pk_fma_f32 v[124:125], v[116:117], v[156:157], v[14:15]
	v_pk_fma_f32 v[126:127], v[118:119], v[158:159], v[16:17]
	v_cvt_pk_bf16_f32 v128, v124, v125
	v_cvt_pk_bf16_f32 v129, v126, v127
	global_store_dwordx2 v[104:105], v[128:129], off offset:1024
	s_waitcnt vmcnt(15)
	v_pk_fma_f32 v[124:125], v[120:121], v[160:161], v[26:27]
	v_pk_fma_f32 v[126:127], v[122:123], v[162:163], v[28:29]
	v_cvt_pk_bf16_f32 v130, v124, v125
	v_cvt_pk_bf16_f32 v131, v126, v127
	global_store_dwordx2 v[104:105], v[130:131], off offset:1536
	s_add_u32 s6, s6, 4
	s_addc_u32 s7, s7, 0
	s_add_u32 s10, s10, 0x4000
	s_addc_u32 s11, s11, 0
	s_cmp_ge_i32 s6, s8
	s_cbranch_scc1 .LBB0_31
	s_branch .LBB0_24
